# on top of previous: load_half_phase issues its 4 row loads together (was load-wait-load-wait serial)
# baseline (speedup 1.0000x reference)
; #define GAS __attribute__((address_space(1)))
; __device__ __forceinline__ int opq_tid() { int t = threadIdx.x; asm volatile("" : "+v"(t)); return t; }
; __device__ __forceinline__ unsigned cvt_pk_bf16(float lo, float hi) { unsigned r; asm volatile("v_cvt_pk_bf16_f32 %0, %1, %2" : "=v"(r) : "v"(lo), "v"(hi)); return r; }
; __device__ __forceinline__ float bf_lo(unsigned w) { return __uint_as_float(w << 16); }
; __device__ __forceinline__ float bf_hi(unsigned w) { return __uint_as_float(w & 0xffff0000u); }
; __device__ __forceinline__ void load_half_phase(const GAS float* xin, GAS bf16_t* xb, GAS float* sso, int G, int cblk) {
;     const int tid = opq_tid(), lane = tid & 63, wave = tid >> 6;
;     for (int row = cblk * 8 + wave; row < TH; row += G * 8) {
;         const GAS f32x4* xr = (const GAS f32x4*)(xin + (size_t)row * D) + lane;
;         GAS u32x2* bo = (GAS u32x2*)(xb + (size_t)row * D) + lane;
;         float s = 0.f;
; #pragma unroll
;         for (int j = 0; j < 4; ++j) { const f32x4 v = xr[64 * j]; u32x2 w; w.x = cvt_pk_bf16(v.x, v.y); w.y = cvt_pk_bf16(v.z, v.w); bo[64 * j] = w;
;             const float a0 = bf_lo(w.x), a1 = bf_hi(w.x), a2 = bf_lo(w.y), a3 = bf_hi(w.y); s += (a0 * a0 + a1 * a1) + (a2 * a2 + a3 * a3); }
;         s = wave_sum(s);
;         if (lane < 16) sso[(size_t)row * 16 + lane] = (lane == 0) ? s : 0.f;
;     }
; }
.LBB0_42:
	s_waitcnt lgkmcnt(0)
	global_load_dwordx4 v[8:11], v[4:5], off offset:-3072
	global_load_dwordx4 v[44:47], v[4:5], off offset:-2048
	global_load_dwordx4 v[48:51], v[4:5], off offset:-1024
	global_load_dwordx4 v[52:55], v[4:5], off
	s_waitcnt vmcnt(0)
	v_cvt_pk_bf16_f32 v12, v8, v9
	v_cvt_pk_bf16_f32 v13, v10, v11
	global_store_dwordx2 v[6:7], v[12:13], off offset:-1024
	v_lshlrev_b32_e32 v19, 16, v12
	v_and_b32_e32 v12, 0xffff0000, v12
	v_lshlrev_b32_e32 v20, 16, v13
	v_and_b32_e32 v13, 0xffff0000, v13
	v_mul_f32_e32 v12, v12, v12
	v_mul_f32_e32 v13, v13, v13
	v_cvt_pk_bf16_f32 v14, v44, v45
	v_cvt_pk_bf16_f32 v15, v46, v47
	v_fmac_f32_e32 v12, v19, v19
	v_fmac_f32_e32 v13, v20, v20
	global_store_dwordx2 v[6:7], v[14:15], off offset:-512
	v_add_f32_e32 v12, v12, v13
	v_lshlrev_b32_e32 v13, 16, v14
	v_and_b32_e32 v14, 0xffff0000, v14
	v_lshlrev_b32_e32 v19, 16, v15
	v_and_b32_e32 v15, 0xffff0000, v15
	v_mul_f32_e32 v14, v14, v14
	v_mul_f32_e32 v15, v15, v15
	v_fmac_f32_e32 v14, v13, v13
	v_fmac_f32_e32 v15, v19, v19
	v_cvt_pk_bf16_f32 v16, v48, v49
	v_add_f32_e32 v13, v14, v15
	v_cvt_pk_bf16_f32 v17, v50, v51
	global_store_dwordx2 v[6:7], v[16:17], off
	v_add_f32_e32 v12, v12, v13
	v_lshlrev_b32_e32 v13, 16, v16
	v_and_b32_e32 v14, 0xffff0000, v16
	v_and_b32_e32 v16, 0xffff0000, v17
	v_lshlrev_b32_e32 v15, 16, v17
	v_mul_f32_e32 v14, v14, v14
	v_mul_f32_e32 v16, v16, v16
	v_fmac_f32_e32 v14, v13, v13
	v_fmac_f32_e32 v16, v15, v15
	v_add_f32_e32 v13, v14, v16
	v_add_f32_e32 v14, v12, v13
	v_cvt_pk_bf16_f32 v12, v52, v53
	v_cvt_pk_bf16_f32 v13, v54, v55
	v_cmp_lt_i32_e64 s[4:5], v249, v253
	v_and_b32_e32 v9, 0xffff0000, v12
	v_and_b32_e32 v11, 0xffff0000, v13
	v_lshlrev_b32_e32 v8, 16, v12
	v_lshlrev_b32_e32 v10, 16, v13
	v_mul_f32_e32 v9, v9, v9
	v_mul_f32_e32 v11, v11, v11
	v_fmac_f32_e32 v9, v8, v8
	v_fmac_f32_e32 v11, v10, v10
	v_cndmask_b32_e64 v18, v246, v249, s[4:5]
	v_add_f32_e32 v8, v9, v11
	v_lshlrev_b32_e32 v18, 2, v18
	v_add_f32_e32 v8, v14, v8
	ds_bpermute_b32 v9, v18, v8
	v_cmp_lt_i32_e64 s[4:5], v250, v253
	global_store_dwordx2 v[6:7], v[12:13], off offset:512
	s_waitcnt lgkmcnt(0)
	v_add_f32_e32 v8, v8, v9
	v_cndmask_b32_e64 v10, v246, v250, s[4:5]
	v_lshlrev_b32_e32 v10, 2, v10
	ds_bpermute_b32 v9, v10, v8
	v_cmp_lt_i32_e64 s[4:5], v182, v253
	s_waitcnt lgkmcnt(0)
	v_add_f32_e32 v8, v8, v9
	v_cndmask_b32_e64 v10, v246, v182, s[4:5]
	v_lshlrev_b32_e32 v10, 2, v10
	ds_bpermute_b32 v9, v10, v8
	v_cmp_lt_i32_e64 s[4:5], v240, v253
	s_waitcnt lgkmcnt(0)
	v_add_f32_e32 v8, v8, v9
	v_cndmask_b32_e64 v10, v246, v240, s[4:5]
	v_lshlrev_b32_e32 v10, 2, v10
	ds_bpermute_b32 v9, v10, v8
	v_cmp_lt_i32_e64 s[4:5], v251, v253
	s_waitcnt lgkmcnt(0)
	v_add_f32_e32 v8, v8, v9
	v_cndmask_b32_e64 v10, v246, v251, s[4:5]
	v_lshlrev_b32_e32 v10, 2, v10
	ds_bpermute_b32 v9, v10, v8
	v_cmp_lt_i32_e64 s[4:5], v252, v253
	s_waitcnt lgkmcnt(0)
	v_add_f32_e32 v8, v8, v9
	v_cndmask_b32_e64 v10, v246, v252, s[4:5]
	v_lshlrev_b32_e32 v9, 2, v10
	ds_bpermute_b32 v9, v9, v8
	s_and_saveexec_b64 s[4:5], vcc
	s_cbranch_execz .LBB0_41
	s_waitcnt lgkmcnt(0)
	v_add_f32_e32 v8, v8, v9
	v_cndmask_b32_e64 v8, 0, v8, s[2:3]
	global_store_dword v[2:3], v8, off
	s_branch .LBB0_41
